# V45 + hand-written hg_prep gate loop (8-token-wide, only b*=f serial) + GDN scan steady-state body with exact vmcnt(56)
# speedup vs baseline: 1.0034x; 1.0034x over previous
.LBB0_883:
	s_lshl_b32 s0, s14, 7
	s_ashr_i32 s33, s14, 2
	s_and_b32 s0, s0, 0x180
	s_and_b32 s1, s14, 0xfffffe00
	s_or_b32 s0, s0, s1
	s_and_b32 s1, s33, 0x7f
	s_or_b32 s0, s0, s1
	s_cmpk_lt_i32 s33, 0x200
	s_cselect_b32 s14, s0, s14
	v_cmp_gt_i32_e32 vcc, s34, v52
	v_cmp_lt_i32_e64 s[0:1], s16, v52
	s_waitcnt lgkmcnt(0)
	s_barrier
	s_and_saveexec_b64 s[24:25], s[0:1]
	s_xor_b64 s[0:1], exec, s[24:25]
	s_ashr_i32 s15, s14, 31
	s_or_saveexec_b64 s[0:1], s[0:1]
	v_mov_b32_e32 v27, 0
	v_mov_b64_e32 v[58:59], s[14:15]
	v_lshlrev_b32_e32 v56, 1, v52
	s_xor_b64 exec, exec, s[0:1]
	s_cbranch_execz .LBB0_901
	v_sub_f32_e32 v26, v60, v53
	v_mul_f32_e32 v26, 0xbfb8aa3b, v26
	v_exp_f32_e32 v26, v26
	s_cmpk_gt_i32 s33, 0x1ff
	s_cselect_b32 s15, 16, 64
	ds_read_u16 v68, v56 offset:18432
	ds_read_u16 v76, v56
	ds_read_u16 v69, v56 offset:18704
	ds_read_u16 v77, v56 offset:272
	ds_read_u16 v70, v56 offset:18976
	ds_read_u16 v78, v56 offset:544
	ds_read_u16 v71, v56 offset:19248
	ds_read_u16 v79, v56 offset:816
	ds_read_u16 v72, v56 offset:19520
	ds_read_u16 v80, v56 offset:1088
	ds_read_u16 v73, v56 offset:19792
	ds_read_u16 v81, v56 offset:1360
	ds_read_u16 v74, v56 offset:20064
	ds_read_u16 v82, v56 offset:1632
	ds_read_u16 v75, v56 offset:20336
	ds_read_u16 v83, v56 offset:1904
	v_add_f32_e32 v26, 1.0, v26
	v_rcp_f32_e32 v53, v26
	v_mov_b32_e32 v27, 1.0
	s_nop 0
	v_sub_f32_e32 v26, 1.0, v53
	s_waitcnt lgkmcnt(0)
	v_lshlrev_b32_e32 v84, 16, v68
	v_lshlrev_b32_e32 v85, 16, v69
	v_lshlrev_b32_e32 v86, 16, v70
	v_lshlrev_b32_e32 v87, 16, v71
	v_lshlrev_b32_e32 v88, 16, v72
	v_lshlrev_b32_e32 v89, 16, v73
	v_lshlrev_b32_e32 v90, 16, v74
	v_lshlrev_b32_e32 v91, 16, v75
	v_lshlrev_b32_e32 v100, 16, v76
	v_lshlrev_b32_e32 v101, 16, v77
	v_lshlrev_b32_e32 v102, 16, v78
	v_lshlrev_b32_e32 v103, 16, v79
	v_lshlrev_b32_e32 v104, 16, v80
	v_lshlrev_b32_e32 v105, 16, v81
	v_lshlrev_b32_e32 v106, 16, v82
	v_lshlrev_b32_e32 v107, 16, v83
	ds_read_u16 v116, v56 offset:20608
	ds_read_u16 v124, v56 offset:2176
	ds_read_u16 v117, v56 offset:20880
	ds_read_u16 v125, v56 offset:2448
	ds_read_u16 v118, v56 offset:21152
	ds_read_u16 v126, v56 offset:2720
	ds_read_u16 v119, v56 offset:21424
	ds_read_u16 v127, v56 offset:2992
	ds_read_u16 v120, v56 offset:21696
	ds_read_u16 v128, v56 offset:3264
	ds_read_u16 v121, v56 offset:21968
	ds_read_u16 v129, v56 offset:3536
	ds_read_u16 v122, v56 offset:22240
	ds_read_u16 v130, v56 offset:3808
	ds_read_u16 v123, v56 offset:22512
	ds_read_u16 v131, v56 offset:4080
	v_mul_f32_e32 v84, 0xbfb8aa3b, v84
	v_mul_f32_e32 v85, 0xbfb8aa3b, v85
	v_mul_f32_e32 v86, 0xbfb8aa3b, v86
	v_mul_f32_e32 v87, 0xbfb8aa3b, v87
	v_mul_f32_e32 v88, 0xbfb8aa3b, v88
	v_mul_f32_e32 v89, 0xbfb8aa3b, v89
	v_mul_f32_e32 v90, 0xbfb8aa3b, v90
	v_mul_f32_e32 v91, 0xbfb8aa3b, v91
	v_mul_f32_e32 v108, 0xbfb8aa3b, v100
	v_mul_f32_e32 v109, 0xbfb8aa3b, v101
	v_mul_f32_e32 v110, 0xbfb8aa3b, v102
	v_mul_f32_e32 v111, 0xbfb8aa3b, v103
	v_mul_f32_e32 v112, 0xbfb8aa3b, v104
	v_mul_f32_e32 v113, 0xbfb8aa3b, v105
	v_mul_f32_e32 v114, 0xbfb8aa3b, v106
	v_mul_f32_e32 v115, 0xbfb8aa3b, v107
	v_exp_f32_e32 v84, v84
	v_exp_f32_e32 v85, v85
	v_exp_f32_e32 v86, v86
	v_exp_f32_e32 v87, v87
	v_exp_f32_e32 v88, v88
	v_exp_f32_e32 v89, v89
	v_exp_f32_e32 v90, v90
	v_exp_f32_e32 v91, v91
	v_exp_f32_e32 v108, v108
	v_exp_f32_e32 v109, v109
	v_exp_f32_e32 v110, v110
	v_exp_f32_e32 v111, v111
	v_exp_f32_e32 v112, v112
	v_exp_f32_e32 v113, v113
	v_exp_f32_e32 v114, v114
	v_exp_f32_e32 v115, v115
	v_add_f32_e32 v84, 1.0, v84
	v_add_f32_e32 v85, 1.0, v85
	v_add_f32_e32 v86, 1.0, v86
	v_add_f32_e32 v87, 1.0, v87
	v_add_f32_e32 v88, 1.0, v88
	v_add_f32_e32 v89, 1.0, v89
	v_add_f32_e32 v90, 1.0, v90
	v_add_f32_e32 v91, 1.0, v91
	v_add_f32_e32 v108, 1.0, v108
	v_add_f32_e32 v109, 1.0, v109
	v_add_f32_e32 v110, 1.0, v110
	v_add_f32_e32 v111, 1.0, v111
	v_add_f32_e32 v112, 1.0, v112
	v_add_f32_e32 v113, 1.0, v113
	v_add_f32_e32 v114, 1.0, v114
	v_add_f32_e32 v115, 1.0, v115
	v_rcp_f32_e32 v84, v84
	v_rcp_f32_e32 v85, v85
	v_rcp_f32_e32 v86, v86
	v_rcp_f32_e32 v87, v87
	v_rcp_f32_e32 v88, v88
	v_rcp_f32_e32 v89, v89
	v_rcp_f32_e32 v90, v90
	v_rcp_f32_e32 v91, v91
	v_rcp_f32_e32 v108, v108
	v_rcp_f32_e32 v109, v109
	v_rcp_f32_e32 v110, v110
	v_rcp_f32_e32 v111, v111
	v_rcp_f32_e32 v112, v112
	v_rcp_f32_e32 v113, v113
	v_rcp_f32_e32 v114, v114
	v_rcp_f32_e32 v115, v115
	v_sub_f32_e32 v92, 1.0, v84
	v_sub_f32_e32 v93, 1.0, v85
	v_sub_f32_e32 v94, 1.0, v86
	v_sub_f32_e32 v95, 1.0, v87
	v_sub_f32_e32 v96, 1.0, v88
	v_sub_f32_e32 v97, 1.0, v89
	v_sub_f32_e32 v98, 1.0, v90
	v_sub_f32_e32 v99, 1.0, v91
	v_fma_f32 v84, v26, v84, v53
	v_fma_f32 v85, v26, v85, v53
	v_fma_f32 v86, v26, v86, v53
	v_fma_f32 v87, v26, v87, v53
	v_fma_f32 v88, v26, v88, v53
	v_fma_f32 v89, v26, v89, v53
	v_fma_f32 v90, v26, v90, v53
	v_fma_f32 v91, v26, v91, v53
	v_mul_f32_e32 v92, v26, v92
	v_mul_f32_e32 v93, v26, v93
	v_mul_f32_e32 v94, v26, v94
	v_mul_f32_e32 v95, v26, v95
	v_mul_f32_e32 v96, v26, v96
	v_mul_f32_e32 v97, v26, v97
	v_mul_f32_e32 v98, v26, v98
	v_mul_f32_e32 v99, v26, v99
	v_mul_f32_e32 v108, v108, v100
	v_mul_f32_e32 v109, v109, v101
	v_mul_f32_e32 v110, v110, v102
	v_mul_f32_e32 v111, v111, v103
	v_mul_f32_e32 v112, v112, v104
	v_mul_f32_e32 v113, v113, v105
	v_mul_f32_e32 v114, v114, v106
	v_mul_f32_e32 v115, v115, v107
	v_mul_f32_e32 v84, v27, v84
	v_mul_f32_e32 v85, v84, v85
	v_mul_f32_e32 v86, v85, v86
	v_mul_f32_e32 v87, v86, v87
	v_mul_f32_e32 v88, v87, v88
	v_mul_f32_e32 v89, v88, v89
	v_mul_f32_e32 v90, v89, v90
	v_mul_f32_e32 v91, v90, v91
	v_mov_b32_e32 v27, v91
	v_rcp_f32_e32 v100, v84
	v_rcp_f32_e32 v101, v85
	v_rcp_f32_e32 v102, v86
	v_rcp_f32_e32 v103, v87
	v_rcp_f32_e32 v104, v88
	v_rcp_f32_e32 v105, v89
	v_rcp_f32_e32 v106, v90
	v_rcp_f32_e32 v107, v91
	v_mul_f32_e32 v108, v84, v108
	v_mul_f32_e32 v109, v85, v109
	v_mul_f32_e32 v110, v86, v110
	v_mul_f32_e32 v111, v87, v111
	v_mul_f32_e32 v112, v88, v112
	v_mul_f32_e32 v113, v89, v113
	v_mul_f32_e32 v114, v90, v114
	v_mul_f32_e32 v115, v91, v115
	v_mul_f32_e32 v92, v92, v100
	v_mul_f32_e32 v93, v93, v101
	v_mul_f32_e32 v94, v94, v102
	v_mul_f32_e32 v95, v95, v103
	v_mul_f32_e32 v96, v96, v104
	v_mul_f32_e32 v97, v97, v105
	v_mul_f32_e32 v98, v98, v106
	v_mul_f32_e32 v99, v99, v107
	v_cvt_pk_bf16_f32 v92, v92, v108
	v_cvt_pk_bf16_f32 v93, v93, v109
	v_cvt_pk_bf16_f32 v94, v94, v110
	v_cvt_pk_bf16_f32 v95, v95, v111
	v_cvt_pk_bf16_f32 v96, v96, v112
	v_cvt_pk_bf16_f32 v97, v97, v113
	v_cvt_pk_bf16_f32 v98, v98, v114
	v_cvt_pk_bf16_f32 v99, v99, v115
	s_waitcnt lgkmcnt(0)
	ds_write_b16_d16_hi v56, v92
	ds_write_b16 v56, v92 offset:18432
	ds_write_b16_d16_hi v56, v93 offset:272
	ds_write_b16 v56, v93 offset:18704
	ds_write_b16_d16_hi v56, v94 offset:544
	ds_write_b16 v56, v94 offset:18976
	ds_write_b16_d16_hi v56, v95 offset:816
	ds_write_b16 v56, v95 offset:19248
	ds_write_b16_d16_hi v56, v96 offset:1088
	ds_write_b16 v56, v96 offset:19520
	ds_write_b16_d16_hi v56, v97 offset:1360
	ds_write_b16 v56, v97 offset:19792
	ds_write_b16_d16_hi v56, v98 offset:1632
	ds_write_b16 v56, v98 offset:20064
	ds_write_b16_d16_hi v56, v99 offset:1904
	ds_write_b16 v56, v99 offset:20336
	v_lshlrev_b32_e32 v84, 16, v116
	v_lshlrev_b32_e32 v85, 16, v117
	v_lshlrev_b32_e32 v86, 16, v118
	v_lshlrev_b32_e32 v87, 16, v119
	v_lshlrev_b32_e32 v88, 16, v120
	v_lshlrev_b32_e32 v89, 16, v121
	v_lshlrev_b32_e32 v90, 16, v122
	v_lshlrev_b32_e32 v91, 16, v123
	v_lshlrev_b32_e32 v100, 16, v124
	v_lshlrev_b32_e32 v101, 16, v125
	v_lshlrev_b32_e32 v102, 16, v126
	v_lshlrev_b32_e32 v103, 16, v127
	v_lshlrev_b32_e32 v104, 16, v128
	v_lshlrev_b32_e32 v105, 16, v129
	v_lshlrev_b32_e32 v106, 16, v130
	v_lshlrev_b32_e32 v107, 16, v131
	ds_read_u16 v68, v56 offset:22784
	ds_read_u16 v76, v56 offset:4352
	ds_read_u16 v69, v56 offset:23056
	ds_read_u16 v77, v56 offset:4624
	ds_read_u16 v70, v56 offset:23328
	ds_read_u16 v78, v56 offset:4896
	ds_read_u16 v71, v56 offset:23600
	ds_read_u16 v79, v56 offset:5168
	ds_read_u16 v72, v56 offset:23872
	ds_read_u16 v80, v56 offset:5440
	ds_read_u16 v73, v56 offset:24144
	ds_read_u16 v81, v56 offset:5712
	ds_read_u16 v74, v56 offset:24416
	ds_read_u16 v82, v56 offset:5984
	ds_read_u16 v75, v56 offset:24688
	ds_read_u16 v83, v56 offset:6256
	v_mul_f32_e32 v84, 0xbfb8aa3b, v84
	v_mul_f32_e32 v85, 0xbfb8aa3b, v85
	v_mul_f32_e32 v86, 0xbfb8aa3b, v86
	v_mul_f32_e32 v87, 0xbfb8aa3b, v87
	v_mul_f32_e32 v88, 0xbfb8aa3b, v88
	v_mul_f32_e32 v89, 0xbfb8aa3b, v89
	v_mul_f32_e32 v90, 0xbfb8aa3b, v90
	v_mul_f32_e32 v91, 0xbfb8aa3b, v91
	v_mul_f32_e32 v108, 0xbfb8aa3b, v100
	v_mul_f32_e32 v109, 0xbfb8aa3b, v101
	v_mul_f32_e32 v110, 0xbfb8aa3b, v102
	v_mul_f32_e32 v111, 0xbfb8aa3b, v103
	v_mul_f32_e32 v112, 0xbfb8aa3b, v104
	v_mul_f32_e32 v113, 0xbfb8aa3b, v105
	v_mul_f32_e32 v114, 0xbfb8aa3b, v106
	v_mul_f32_e32 v115, 0xbfb8aa3b, v107
	v_exp_f32_e32 v84, v84
	v_exp_f32_e32 v85, v85
	v_exp_f32_e32 v86, v86
	v_exp_f32_e32 v87, v87
	v_exp_f32_e32 v88, v88
	v_exp_f32_e32 v89, v89
	v_exp_f32_e32 v90, v90
	v_exp_f32_e32 v91, v91
	v_exp_f32_e32 v108, v108
	v_exp_f32_e32 v109, v109
	v_exp_f32_e32 v110, v110
	v_exp_f32_e32 v111, v111
	v_exp_f32_e32 v112, v112
	v_exp_f32_e32 v113, v113
	v_exp_f32_e32 v114, v114
	v_exp_f32_e32 v115, v115
	v_add_f32_e32 v84, 1.0, v84
	v_add_f32_e32 v85, 1.0, v85
	v_add_f32_e32 v86, 1.0, v86
	v_add_f32_e32 v87, 1.0, v87
	v_add_f32_e32 v88, 1.0, v88
	v_add_f32_e32 v89, 1.0, v89
	v_add_f32_e32 v90, 1.0, v90
	v_add_f32_e32 v91, 1.0, v91
	v_add_f32_e32 v108, 1.0, v108
	v_add_f32_e32 v109, 1.0, v109
	v_add_f32_e32 v110, 1.0, v110
	v_add_f32_e32 v111, 1.0, v111
	v_add_f32_e32 v112, 1.0, v112
	v_add_f32_e32 v113, 1.0, v113
	v_add_f32_e32 v114, 1.0, v114
	v_add_f32_e32 v115, 1.0, v115
	v_rcp_f32_e32 v84, v84
	v_rcp_f32_e32 v85, v85
	v_rcp_f32_e32 v86, v86
	v_rcp_f32_e32 v87, v87
	v_rcp_f32_e32 v88, v88
	v_rcp_f32_e32 v89, v89
	v_rcp_f32_e32 v90, v90
	v_rcp_f32_e32 v91, v91
	v_rcp_f32_e32 v108, v108
	v_rcp_f32_e32 v109, v109
	v_rcp_f32_e32 v110, v110
	v_rcp_f32_e32 v111, v111
	v_rcp_f32_e32 v112, v112
	v_rcp_f32_e32 v113, v113
	v_rcp_f32_e32 v114, v114
	v_rcp_f32_e32 v115, v115
	v_sub_f32_e32 v92, 1.0, v84
	v_sub_f32_e32 v93, 1.0, v85
	v_sub_f32_e32 v94, 1.0, v86
	v_sub_f32_e32 v95, 1.0, v87
	v_sub_f32_e32 v96, 1.0, v88
	v_sub_f32_e32 v97, 1.0, v89
	v_sub_f32_e32 v98, 1.0, v90
	v_sub_f32_e32 v99, 1.0, v91
	v_fma_f32 v84, v26, v84, v53
	v_fma_f32 v85, v26, v85, v53
	v_fma_f32 v86, v26, v86, v53
	v_fma_f32 v87, v26, v87, v53
	v_fma_f32 v88, v26, v88, v53
	v_fma_f32 v89, v26, v89, v53
	v_fma_f32 v90, v26, v90, v53
	v_fma_f32 v91, v26, v91, v53
	v_mul_f32_e32 v92, v26, v92
	v_mul_f32_e32 v93, v26, v93
	v_mul_f32_e32 v94, v26, v94
	v_mul_f32_e32 v95, v26, v95
	v_mul_f32_e32 v96, v26, v96
	v_mul_f32_e32 v97, v26, v97
	v_mul_f32_e32 v98, v26, v98
	v_mul_f32_e32 v99, v26, v99
	v_mul_f32_e32 v108, v108, v100
	v_mul_f32_e32 v109, v109, v101
	v_mul_f32_e32 v110, v110, v102
	v_mul_f32_e32 v111, v111, v103
	v_mul_f32_e32 v112, v112, v104
	v_mul_f32_e32 v113, v113, v105
	v_mul_f32_e32 v114, v114, v106
	v_mul_f32_e32 v115, v115, v107
	v_mul_f32_e32 v84, v27, v84
	v_mul_f32_e32 v85, v84, v85
	v_mul_f32_e32 v86, v85, v86
	v_mul_f32_e32 v87, v86, v87
	v_mul_f32_e32 v88, v87, v88
	v_mul_f32_e32 v89, v88, v89
	v_mul_f32_e32 v90, v89, v90
	v_mul_f32_e32 v91, v90, v91
	v_mov_b32_e32 v27, v91
	v_rcp_f32_e32 v100, v84
	v_rcp_f32_e32 v101, v85
	v_rcp_f32_e32 v102, v86
	v_rcp_f32_e32 v103, v87
	v_rcp_f32_e32 v104, v88
	v_rcp_f32_e32 v105, v89
	v_rcp_f32_e32 v106, v90
	v_rcp_f32_e32 v107, v91
	v_mul_f32_e32 v108, v84, v108
	v_mul_f32_e32 v109, v85, v109
	v_mul_f32_e32 v110, v86, v110
	v_mul_f32_e32 v111, v87, v111
	v_mul_f32_e32 v112, v88, v112
	v_mul_f32_e32 v113, v89, v113
	v_mul_f32_e32 v114, v90, v114
	v_mul_f32_e32 v115, v91, v115
	v_mul_f32_e32 v92, v92, v100
	v_mul_f32_e32 v93, v93, v101
	v_mul_f32_e32 v94, v94, v102
	v_mul_f32_e32 v95, v95, v103
	v_mul_f32_e32 v96, v96, v104
	v_mul_f32_e32 v97, v97, v105
	v_mul_f32_e32 v98, v98, v106
	v_mul_f32_e32 v99, v99, v107
	v_cvt_pk_bf16_f32 v92, v92, v108
	v_cvt_pk_bf16_f32 v93, v93, v109
	v_cvt_pk_bf16_f32 v94, v94, v110
	v_cvt_pk_bf16_f32 v95, v95, v111
	v_cvt_pk_bf16_f32 v96, v96, v112
	v_cvt_pk_bf16_f32 v97, v97, v113
	v_cvt_pk_bf16_f32 v98, v98, v114
	v_cvt_pk_bf16_f32 v99, v99, v115
	s_waitcnt lgkmcnt(0)
	ds_write_b16_d16_hi v56, v92 offset:2176
	ds_write_b16 v56, v92 offset:20608
	ds_write_b16_d16_hi v56, v93 offset:2448
	ds_write_b16 v56, v93 offset:20880
	ds_write_b16_d16_hi v56, v94 offset:2720
	ds_write_b16 v56, v94 offset:21152
	ds_write_b16_d16_hi v56, v95 offset:2992
	ds_write_b16 v56, v95 offset:21424
	ds_write_b16_d16_hi v56, v96 offset:3264
	ds_write_b16 v56, v96 offset:21696
	ds_write_b16_d16_hi v56, v97 offset:3536
	ds_write_b16 v56, v97 offset:21968
	ds_write_b16_d16_hi v56, v98 offset:3808
	ds_write_b16 v56, v98 offset:22240
	ds_write_b16_d16_hi v56, v99 offset:4080
	ds_write_b16 v56, v99 offset:22512
	s_cmp_eq_u32 s15, 16
	s_cbranch_scc1 .Lhp_zero
	v_lshlrev_b32_e32 v84, 16, v68
	v_lshlrev_b32_e32 v85, 16, v69
	v_lshlrev_b32_e32 v86, 16, v70
	v_lshlrev_b32_e32 v87, 16, v71
	v_lshlrev_b32_e32 v88, 16, v72
	v_lshlrev_b32_e32 v89, 16, v73
	v_lshlrev_b32_e32 v90, 16, v74
	v_lshlrev_b32_e32 v91, 16, v75
	v_lshlrev_b32_e32 v100, 16, v76
	v_lshlrev_b32_e32 v101, 16, v77
	v_lshlrev_b32_e32 v102, 16, v78
	v_lshlrev_b32_e32 v103, 16, v79
	v_lshlrev_b32_e32 v104, 16, v80
	v_lshlrev_b32_e32 v105, 16, v81
	v_lshlrev_b32_e32 v106, 16, v82
	v_lshlrev_b32_e32 v107, 16, v83
	ds_read_u16 v116, v56 offset:24960
	ds_read_u16 v124, v56 offset:6528
	ds_read_u16 v117, v56 offset:25232
	ds_read_u16 v125, v56 offset:6800
	ds_read_u16 v118, v56 offset:25504
	ds_read_u16 v126, v56 offset:7072
	ds_read_u16 v119, v56 offset:25776
	ds_read_u16 v127, v56 offset:7344
	ds_read_u16 v120, v56 offset:26048
	ds_read_u16 v128, v56 offset:7616
	ds_read_u16 v121, v56 offset:26320
	ds_read_u16 v129, v56 offset:7888
	ds_read_u16 v122, v56 offset:26592
	ds_read_u16 v130, v56 offset:8160
	ds_read_u16 v123, v56 offset:26864
	ds_read_u16 v131, v56 offset:8432
	v_mul_f32_e32 v84, 0xbfb8aa3b, v84
	v_mul_f32_e32 v85, 0xbfb8aa3b, v85
	v_mul_f32_e32 v86, 0xbfb8aa3b, v86
	v_mul_f32_e32 v87, 0xbfb8aa3b, v87
	v_mul_f32_e32 v88, 0xbfb8aa3b, v88
	v_mul_f32_e32 v89, 0xbfb8aa3b, v89
	v_mul_f32_e32 v90, 0xbfb8aa3b, v90
	v_mul_f32_e32 v91, 0xbfb8aa3b, v91
	v_mul_f32_e32 v108, 0xbfb8aa3b, v100
	v_mul_f32_e32 v109, 0xbfb8aa3b, v101
	v_mul_f32_e32 v110, 0xbfb8aa3b, v102
	v_mul_f32_e32 v111, 0xbfb8aa3b, v103
	v_mul_f32_e32 v112, 0xbfb8aa3b, v104
	v_mul_f32_e32 v113, 0xbfb8aa3b, v105
	v_mul_f32_e32 v114, 0xbfb8aa3b, v106
	v_mul_f32_e32 v115, 0xbfb8aa3b, v107
	v_exp_f32_e32 v84, v84
	v_exp_f32_e32 v85, v85
	v_exp_f32_e32 v86, v86
	v_exp_f32_e32 v87, v87
	v_exp_f32_e32 v88, v88
	v_exp_f32_e32 v89, v89
	v_exp_f32_e32 v90, v90
	v_exp_f32_e32 v91, v91
	v_exp_f32_e32 v108, v108
	v_exp_f32_e32 v109, v109
	v_exp_f32_e32 v110, v110
	v_exp_f32_e32 v111, v111
	v_exp_f32_e32 v112, v112
	v_exp_f32_e32 v113, v113
	v_exp_f32_e32 v114, v114
	v_exp_f32_e32 v115, v115
	v_add_f32_e32 v84, 1.0, v84
	v_add_f32_e32 v85, 1.0, v85
	v_add_f32_e32 v86, 1.0, v86
	v_add_f32_e32 v87, 1.0, v87
	v_add_f32_e32 v88, 1.0, v88
	v_add_f32_e32 v89, 1.0, v89
	v_add_f32_e32 v90, 1.0, v90
	v_add_f32_e32 v91, 1.0, v91
	v_add_f32_e32 v108, 1.0, v108
	v_add_f32_e32 v109, 1.0, v109
	v_add_f32_e32 v110, 1.0, v110
	v_add_f32_e32 v111, 1.0, v111
	v_add_f32_e32 v112, 1.0, v112
	v_add_f32_e32 v113, 1.0, v113
	v_add_f32_e32 v114, 1.0, v114
	v_add_f32_e32 v115, 1.0, v115
	v_rcp_f32_e32 v84, v84
	v_rcp_f32_e32 v85, v85
	v_rcp_f32_e32 v86, v86
	v_rcp_f32_e32 v87, v87
	v_rcp_f32_e32 v88, v88
	v_rcp_f32_e32 v89, v89
	v_rcp_f32_e32 v90, v90
	v_rcp_f32_e32 v91, v91
	v_rcp_f32_e32 v108, v108
	v_rcp_f32_e32 v109, v109
	v_rcp_f32_e32 v110, v110
	v_rcp_f32_e32 v111, v111
	v_rcp_f32_e32 v112, v112
	v_rcp_f32_e32 v113, v113
	v_rcp_f32_e32 v114, v114
	v_rcp_f32_e32 v115, v115
	v_sub_f32_e32 v92, 1.0, v84
	v_sub_f32_e32 v93, 1.0, v85
	v_sub_f32_e32 v94, 1.0, v86
	v_sub_f32_e32 v95, 1.0, v87
	v_sub_f32_e32 v96, 1.0, v88
	v_sub_f32_e32 v97, 1.0, v89
	v_sub_f32_e32 v98, 1.0, v90
	v_sub_f32_e32 v99, 1.0, v91
	v_fma_f32 v84, v26, v84, v53
	v_fma_f32 v85, v26, v85, v53
	v_fma_f32 v86, v26, v86, v53
	v_fma_f32 v87, v26, v87, v53
	v_fma_f32 v88, v26, v88, v53
	v_fma_f32 v89, v26, v89, v53
	v_fma_f32 v90, v26, v90, v53
	v_fma_f32 v91, v26, v91, v53
	v_mul_f32_e32 v92, v26, v92
	v_mul_f32_e32 v93, v26, v93
	v_mul_f32_e32 v94, v26, v94
	v_mul_f32_e32 v95, v26, v95
	v_mul_f32_e32 v96, v26, v96
	v_mul_f32_e32 v97, v26, v97
	v_mul_f32_e32 v98, v26, v98
	v_mul_f32_e32 v99, v26, v99
	v_mul_f32_e32 v108, v108, v100
	v_mul_f32_e32 v109, v109, v101
	v_mul_f32_e32 v110, v110, v102
	v_mul_f32_e32 v111, v111, v103
	v_mul_f32_e32 v112, v112, v104
	v_mul_f32_e32 v113, v113, v105
	v_mul_f32_e32 v114, v114, v106
	v_mul_f32_e32 v115, v115, v107
	v_mul_f32_e32 v84, v27, v84
	v_mul_f32_e32 v85, v84, v85
	v_mul_f32_e32 v86, v85, v86
	v_mul_f32_e32 v87, v86, v87
	v_mul_f32_e32 v88, v87, v88
	v_mul_f32_e32 v89, v88, v89
	v_mul_f32_e32 v90, v89, v90
	v_mul_f32_e32 v91, v90, v91
	v_mov_b32_e32 v27, v91
	v_rcp_f32_e32 v100, v84
	v_rcp_f32_e32 v101, v85
	v_rcp_f32_e32 v102, v86
	v_rcp_f32_e32 v103, v87
	v_rcp_f32_e32 v104, v88
	v_rcp_f32_e32 v105, v89
	v_rcp_f32_e32 v106, v90
	v_rcp_f32_e32 v107, v91
	v_mul_f32_e32 v108, v84, v108
	v_mul_f32_e32 v109, v85, v109
	v_mul_f32_e32 v110, v86, v110
	v_mul_f32_e32 v111, v87, v111
	v_mul_f32_e32 v112, v88, v112
	v_mul_f32_e32 v113, v89, v113
	v_mul_f32_e32 v114, v90, v114
	v_mul_f32_e32 v115, v91, v115
	v_mul_f32_e32 v92, v92, v100
	v_mul_f32_e32 v93, v93, v101
	v_mul_f32_e32 v94, v94, v102
	v_mul_f32_e32 v95, v95, v103
	v_mul_f32_e32 v96, v96, v104
	v_mul_f32_e32 v97, v97, v105
	v_mul_f32_e32 v98, v98, v106
	v_mul_f32_e32 v99, v99, v107
	v_cvt_pk_bf16_f32 v92, v92, v108
	v_cvt_pk_bf16_f32 v93, v93, v109
	v_cvt_pk_bf16_f32 v94, v94, v110
	v_cvt_pk_bf16_f32 v95, v95, v111
	v_cvt_pk_bf16_f32 v96, v96, v112
	v_cvt_pk_bf16_f32 v97, v97, v113
	v_cvt_pk_bf16_f32 v98, v98, v114
	v_cvt_pk_bf16_f32 v99, v99, v115
	s_waitcnt lgkmcnt(0)
	ds_write_b16_d16_hi v56, v92 offset:4352
	ds_write_b16 v56, v92 offset:22784
	ds_write_b16_d16_hi v56, v93 offset:4624
	ds_write_b16 v56, v93 offset:23056
	ds_write_b16_d16_hi v56, v94 offset:4896
	ds_write_b16 v56, v94 offset:23328
	ds_write_b16_d16_hi v56, v95 offset:5168
	ds_write_b16 v56, v95 offset:23600
	ds_write_b16_d16_hi v56, v96 offset:5440
	ds_write_b16 v56, v96 offset:23872
	ds_write_b16_d16_hi v56, v97 offset:5712
	ds_write_b16 v56, v97 offset:24144
	ds_write_b16_d16_hi v56, v98 offset:5984
	ds_write_b16 v56, v98 offset:24416
	ds_write_b16_d16_hi v56, v99 offset:6256
	ds_write_b16 v56, v99 offset:24688
	v_lshlrev_b32_e32 v84, 16, v116
	v_lshlrev_b32_e32 v85, 16, v117
	v_lshlrev_b32_e32 v86, 16, v118
	v_lshlrev_b32_e32 v87, 16, v119
	v_lshlrev_b32_e32 v88, 16, v120
	v_lshlrev_b32_e32 v89, 16, v121
	v_lshlrev_b32_e32 v90, 16, v122
	v_lshlrev_b32_e32 v91, 16, v123
	v_lshlrev_b32_e32 v100, 16, v124
	v_lshlrev_b32_e32 v101, 16, v125
	v_lshlrev_b32_e32 v102, 16, v126
	v_lshlrev_b32_e32 v103, 16, v127
	v_lshlrev_b32_e32 v104, 16, v128
	v_lshlrev_b32_e32 v105, 16, v129
	v_lshlrev_b32_e32 v106, 16, v130
	v_lshlrev_b32_e32 v107, 16, v131
	ds_read_u16 v68, v56 offset:27136
	ds_read_u16 v76, v56 offset:8704
	ds_read_u16 v69, v56 offset:27408
	ds_read_u16 v77, v56 offset:8976
	ds_read_u16 v70, v56 offset:27680
	ds_read_u16 v78, v56 offset:9248
	ds_read_u16 v71, v56 offset:27952
	ds_read_u16 v79, v56 offset:9520
	ds_read_u16 v72, v56 offset:28224
	ds_read_u16 v80, v56 offset:9792
	ds_read_u16 v73, v56 offset:28496
	ds_read_u16 v81, v56 offset:10064
	ds_read_u16 v74, v56 offset:28768
	ds_read_u16 v82, v56 offset:10336
	ds_read_u16 v75, v56 offset:29040
	ds_read_u16 v83, v56 offset:10608
	v_mul_f32_e32 v84, 0xbfb8aa3b, v84
	v_mul_f32_e32 v85, 0xbfb8aa3b, v85
	v_mul_f32_e32 v86, 0xbfb8aa3b, v86
	v_mul_f32_e32 v87, 0xbfb8aa3b, v87
	v_mul_f32_e32 v88, 0xbfb8aa3b, v88
	v_mul_f32_e32 v89, 0xbfb8aa3b, v89
	v_mul_f32_e32 v90, 0xbfb8aa3b, v90
	v_mul_f32_e32 v91, 0xbfb8aa3b, v91
	v_mul_f32_e32 v108, 0xbfb8aa3b, v100
	v_mul_f32_e32 v109, 0xbfb8aa3b, v101
	v_mul_f32_e32 v110, 0xbfb8aa3b, v102
	v_mul_f32_e32 v111, 0xbfb8aa3b, v103
	v_mul_f32_e32 v112, 0xbfb8aa3b, v104
	v_mul_f32_e32 v113, 0xbfb8aa3b, v105
	v_mul_f32_e32 v114, 0xbfb8aa3b, v106
	v_mul_f32_e32 v115, 0xbfb8aa3b, v107
	v_exp_f32_e32 v84, v84
	v_exp_f32_e32 v85, v85
	v_exp_f32_e32 v86, v86
	v_exp_f32_e32 v87, v87
	v_exp_f32_e32 v88, v88
	v_exp_f32_e32 v89, v89
	v_exp_f32_e32 v90, v90
	v_exp_f32_e32 v91, v91
	v_exp_f32_e32 v108, v108
	v_exp_f32_e32 v109, v109
	v_exp_f32_e32 v110, v110
	v_exp_f32_e32 v111, v111
	v_exp_f32_e32 v112, v112
	v_exp_f32_e32 v113, v113
	v_exp_f32_e32 v114, v114
	v_exp_f32_e32 v115, v115
	v_add_f32_e32 v84, 1.0, v84
	v_add_f32_e32 v85, 1.0, v85
	v_add_f32_e32 v86, 1.0, v86
	v_add_f32_e32 v87, 1.0, v87
	v_add_f32_e32 v88, 1.0, v88
	v_add_f32_e32 v89, 1.0, v89
	v_add_f32_e32 v90, 1.0, v90
	v_add_f32_e32 v91, 1.0, v91
	v_add_f32_e32 v108, 1.0, v108
	v_add_f32_e32 v109, 1.0, v109
	v_add_f32_e32 v110, 1.0, v110
	v_add_f32_e32 v111, 1.0, v111
	v_add_f32_e32 v112, 1.0, v112
	v_add_f32_e32 v113, 1.0, v113
	v_add_f32_e32 v114, 1.0, v114
	v_add_f32_e32 v115, 1.0, v115
	v_rcp_f32_e32 v84, v84
	v_rcp_f32_e32 v85, v85
	v_rcp_f32_e32 v86, v86
	v_rcp_f32_e32 v87, v87
	v_rcp_f32_e32 v88, v88
	v_rcp_f32_e32 v89, v89
	v_rcp_f32_e32 v90, v90
	v_rcp_f32_e32 v91, v91
	v_rcp_f32_e32 v108, v108
	v_rcp_f32_e32 v109, v109
	v_rcp_f32_e32 v110, v110
	v_rcp_f32_e32 v111, v111
	v_rcp_f32_e32 v112, v112
	v_rcp_f32_e32 v113, v113
	v_rcp_f32_e32 v114, v114
	v_rcp_f32_e32 v115, v115
	v_sub_f32_e32 v92, 1.0, v84
	v_sub_f32_e32 v93, 1.0, v85
	v_sub_f32_e32 v94, 1.0, v86
	v_sub_f32_e32 v95, 1.0, v87
	v_sub_f32_e32 v96, 1.0, v88
	v_sub_f32_e32 v97, 1.0, v89
	v_sub_f32_e32 v98, 1.0, v90
	v_sub_f32_e32 v99, 1.0, v91
	v_fma_f32 v84, v26, v84, v53
	v_fma_f32 v85, v26, v85, v53
	v_fma_f32 v86, v26, v86, v53
	v_fma_f32 v87, v26, v87, v53
	v_fma_f32 v88, v26, v88, v53
	v_fma_f32 v89, v26, v89, v53
	v_fma_f32 v90, v26, v90, v53
	v_fma_f32 v91, v26, v91, v53
	v_mul_f32_e32 v92, v26, v92
	v_mul_f32_e32 v93, v26, v93
	v_mul_f32_e32 v94, v26, v94
	v_mul_f32_e32 v95, v26, v95
	v_mul_f32_e32 v96, v26, v96
	v_mul_f32_e32 v97, v26, v97
	v_mul_f32_e32 v98, v26, v98
	v_mul_f32_e32 v99, v26, v99
	v_mul_f32_e32 v108, v108, v100
	v_mul_f32_e32 v109, v109, v101
	v_mul_f32_e32 v110, v110, v102
	v_mul_f32_e32 v111, v111, v103
	v_mul_f32_e32 v112, v112, v104
	v_mul_f32_e32 v113, v113, v105
	v_mul_f32_e32 v114, v114, v106
	v_mul_f32_e32 v115, v115, v107
	v_mul_f32_e32 v84, v27, v84
	v_mul_f32_e32 v85, v84, v85
	v_mul_f32_e32 v86, v85, v86
	v_mul_f32_e32 v87, v86, v87
	v_mul_f32_e32 v88, v87, v88
	v_mul_f32_e32 v89, v88, v89
	v_mul_f32_e32 v90, v89, v90
	v_mul_f32_e32 v91, v90, v91
	v_mov_b32_e32 v27, v91
	v_rcp_f32_e32 v100, v84
	v_rcp_f32_e32 v101, v85
	v_rcp_f32_e32 v102, v86
	v_rcp_f32_e32 v103, v87
	v_rcp_f32_e32 v104, v88
	v_rcp_f32_e32 v105, v89
	v_rcp_f32_e32 v106, v90
	v_rcp_f32_e32 v107, v91
	v_mul_f32_e32 v108, v84, v108
	v_mul_f32_e32 v109, v85, v109
	v_mul_f32_e32 v110, v86, v110
	v_mul_f32_e32 v111, v87, v111
	v_mul_f32_e32 v112, v88, v112
	v_mul_f32_e32 v113, v89, v113
	v_mul_f32_e32 v114, v90, v114
	v_mul_f32_e32 v115, v91, v115
	v_mul_f32_e32 v92, v92, v100
	v_mul_f32_e32 v93, v93, v101
	v_mul_f32_e32 v94, v94, v102
	v_mul_f32_e32 v95, v95, v103
	v_mul_f32_e32 v96, v96, v104
	v_mul_f32_e32 v97, v97, v105
	v_mul_f32_e32 v98, v98, v106
	v_mul_f32_e32 v99, v99, v107
	v_cvt_pk_bf16_f32 v92, v92, v108
	v_cvt_pk_bf16_f32 v93, v93, v109
	v_cvt_pk_bf16_f32 v94, v94, v110
	v_cvt_pk_bf16_f32 v95, v95, v111
	v_cvt_pk_bf16_f32 v96, v96, v112
	v_cvt_pk_bf16_f32 v97, v97, v113
	v_cvt_pk_bf16_f32 v98, v98, v114
	v_cvt_pk_bf16_f32 v99, v99, v115
	s_waitcnt lgkmcnt(0)
	ds_write_b16_d16_hi v56, v92 offset:6528
	ds_write_b16 v56, v92 offset:24960
	ds_write_b16_d16_hi v56, v93 offset:6800
	ds_write_b16 v56, v93 offset:25232
	ds_write_b16_d16_hi v56, v94 offset:7072
	ds_write_b16 v56, v94 offset:25504
	ds_write_b16_d16_hi v56, v95 offset:7344
	ds_write_b16 v56, v95 offset:25776
	ds_write_b16_d16_hi v56, v96 offset:7616
	ds_write_b16 v56, v96 offset:26048
	ds_write_b16_d16_hi v56, v97 offset:7888
	ds_write_b16 v56, v97 offset:26320
	ds_write_b16_d16_hi v56, v98 offset:8160
	ds_write_b16 v56, v98 offset:26592
	ds_write_b16_d16_hi v56, v99 offset:8432
	ds_write_b16 v56, v99 offset:26864
	v_lshlrev_b32_e32 v84, 16, v68
	v_lshlrev_b32_e32 v85, 16, v69
	v_lshlrev_b32_e32 v86, 16, v70
	v_lshlrev_b32_e32 v87, 16, v71
	v_lshlrev_b32_e32 v88, 16, v72
	v_lshlrev_b32_e32 v89, 16, v73
	v_lshlrev_b32_e32 v90, 16, v74
	v_lshlrev_b32_e32 v91, 16, v75
	v_lshlrev_b32_e32 v100, 16, v76
	v_lshlrev_b32_e32 v101, 16, v77
	v_lshlrev_b32_e32 v102, 16, v78
	v_lshlrev_b32_e32 v103, 16, v79
	v_lshlrev_b32_e32 v104, 16, v80
	v_lshlrev_b32_e32 v105, 16, v81
	v_lshlrev_b32_e32 v106, 16, v82
	v_lshlrev_b32_e32 v107, 16, v83
	ds_read_u16 v116, v56 offset:29312
	ds_read_u16 v124, v56 offset:10880
	ds_read_u16 v117, v56 offset:29584
	ds_read_u16 v125, v56 offset:11152
	ds_read_u16 v118, v56 offset:29856
	ds_read_u16 v126, v56 offset:11424
	ds_read_u16 v119, v56 offset:30128
	ds_read_u16 v127, v56 offset:11696
	ds_read_u16 v120, v56 offset:30400
	ds_read_u16 v128, v56 offset:11968
	ds_read_u16 v121, v56 offset:30672
	ds_read_u16 v129, v56 offset:12240
	ds_read_u16 v122, v56 offset:30944
	ds_read_u16 v130, v56 offset:12512
	ds_read_u16 v123, v56 offset:31216
	ds_read_u16 v131, v56 offset:12784
	v_mul_f32_e32 v84, 0xbfb8aa3b, v84
	v_mul_f32_e32 v85, 0xbfb8aa3b, v85
	v_mul_f32_e32 v86, 0xbfb8aa3b, v86
	v_mul_f32_e32 v87, 0xbfb8aa3b, v87
	v_mul_f32_e32 v88, 0xbfb8aa3b, v88
	v_mul_f32_e32 v89, 0xbfb8aa3b, v89
	v_mul_f32_e32 v90, 0xbfb8aa3b, v90
	v_mul_f32_e32 v91, 0xbfb8aa3b, v91
	v_mul_f32_e32 v108, 0xbfb8aa3b, v100
	v_mul_f32_e32 v109, 0xbfb8aa3b, v101
	v_mul_f32_e32 v110, 0xbfb8aa3b, v102
	v_mul_f32_e32 v111, 0xbfb8aa3b, v103
	v_mul_f32_e32 v112, 0xbfb8aa3b, v104
	v_mul_f32_e32 v113, 0xbfb8aa3b, v105
	v_mul_f32_e32 v114, 0xbfb8aa3b, v106
	v_mul_f32_e32 v115, 0xbfb8aa3b, v107
	v_exp_f32_e32 v84, v84
	v_exp_f32_e32 v85, v85
	v_exp_f32_e32 v86, v86
	v_exp_f32_e32 v87, v87
	v_exp_f32_e32 v88, v88
	v_exp_f32_e32 v89, v89
	v_exp_f32_e32 v90, v90
	v_exp_f32_e32 v91, v91
	v_exp_f32_e32 v108, v108
	v_exp_f32_e32 v109, v109
	v_exp_f32_e32 v110, v110
	v_exp_f32_e32 v111, v111
	v_exp_f32_e32 v112, v112
	v_exp_f32_e32 v113, v113
	v_exp_f32_e32 v114, v114
	v_exp_f32_e32 v115, v115
	v_add_f32_e32 v84, 1.0, v84
	v_add_f32_e32 v85, 1.0, v85
	v_add_f32_e32 v86, 1.0, v86
	v_add_f32_e32 v87, 1.0, v87
	v_add_f32_e32 v88, 1.0, v88
	v_add_f32_e32 v89, 1.0, v89
	v_add_f32_e32 v90, 1.0, v90
	v_add_f32_e32 v91, 1.0, v91
	v_add_f32_e32 v108, 1.0, v108
	v_add_f32_e32 v109, 1.0, v109
	v_add_f32_e32 v110, 1.0, v110
	v_add_f32_e32 v111, 1.0, v111
	v_add_f32_e32 v112, 1.0, v112
	v_add_f32_e32 v113, 1.0, v113
	v_add_f32_e32 v114, 1.0, v114
	v_add_f32_e32 v115, 1.0, v115
	v_rcp_f32_e32 v84, v84
	v_rcp_f32_e32 v85, v85
	v_rcp_f32_e32 v86, v86
	v_rcp_f32_e32 v87, v87
	v_rcp_f32_e32 v88, v88
	v_rcp_f32_e32 v89, v89
	v_rcp_f32_e32 v90, v90
	v_rcp_f32_e32 v91, v91
	v_rcp_f32_e32 v108, v108
	v_rcp_f32_e32 v109, v109
	v_rcp_f32_e32 v110, v110
	v_rcp_f32_e32 v111, v111
	v_rcp_f32_e32 v112, v112
	v_rcp_f32_e32 v113, v113
	v_rcp_f32_e32 v114, v114
	v_rcp_f32_e32 v115, v115
	v_sub_f32_e32 v92, 1.0, v84
	v_sub_f32_e32 v93, 1.0, v85
	v_sub_f32_e32 v94, 1.0, v86
	v_sub_f32_e32 v95, 1.0, v87
	v_sub_f32_e32 v96, 1.0, v88
	v_sub_f32_e32 v97, 1.0, v89
	v_sub_f32_e32 v98, 1.0, v90
	v_sub_f32_e32 v99, 1.0, v91
	v_fma_f32 v84, v26, v84, v53
	v_fma_f32 v85, v26, v85, v53
	v_fma_f32 v86, v26, v86, v53
	v_fma_f32 v87, v26, v87, v53
	v_fma_f32 v88, v26, v88, v53
	v_fma_f32 v89, v26, v89, v53
	v_fma_f32 v90, v26, v90, v53
	v_fma_f32 v91, v26, v91, v53
	v_mul_f32_e32 v92, v26, v92
	v_mul_f32_e32 v93, v26, v93
	v_mul_f32_e32 v94, v26, v94
	v_mul_f32_e32 v95, v26, v95
	v_mul_f32_e32 v96, v26, v96
	v_mul_f32_e32 v97, v26, v97
	v_mul_f32_e32 v98, v26, v98
	v_mul_f32_e32 v99, v26, v99
	v_mul_f32_e32 v108, v108, v100
	v_mul_f32_e32 v109, v109, v101
	v_mul_f32_e32 v110, v110, v102
	v_mul_f32_e32 v111, v111, v103
	v_mul_f32_e32 v112, v112, v104
	v_mul_f32_e32 v113, v113, v105
	v_mul_f32_e32 v114, v114, v106
	v_mul_f32_e32 v115, v115, v107
	v_mul_f32_e32 v84, v27, v84
	v_mul_f32_e32 v85, v84, v85
	v_mul_f32_e32 v86, v85, v86
	v_mul_f32_e32 v87, v86, v87
	v_mul_f32_e32 v88, v87, v88
	v_mul_f32_e32 v89, v88, v89
	v_mul_f32_e32 v90, v89, v90
	v_mul_f32_e32 v91, v90, v91
	v_mov_b32_e32 v27, v91
	v_rcp_f32_e32 v100, v84
	v_rcp_f32_e32 v101, v85
	v_rcp_f32_e32 v102, v86
	v_rcp_f32_e32 v103, v87
	v_rcp_f32_e32 v104, v88
	v_rcp_f32_e32 v105, v89
	v_rcp_f32_e32 v106, v90
	v_rcp_f32_e32 v107, v91
	v_mul_f32_e32 v108, v84, v108
	v_mul_f32_e32 v109, v85, v109
	v_mul_f32_e32 v110, v86, v110
	v_mul_f32_e32 v111, v87, v111
	v_mul_f32_e32 v112, v88, v112
	v_mul_f32_e32 v113, v89, v113
	v_mul_f32_e32 v114, v90, v114
	v_mul_f32_e32 v115, v91, v115
	v_mul_f32_e32 v92, v92, v100
	v_mul_f32_e32 v93, v93, v101
	v_mul_f32_e32 v94, v94, v102
	v_mul_f32_e32 v95, v95, v103
	v_mul_f32_e32 v96, v96, v104
	v_mul_f32_e32 v97, v97, v105
	v_mul_f32_e32 v98, v98, v106
	v_mul_f32_e32 v99, v99, v107
	v_cvt_pk_bf16_f32 v92, v92, v108
	v_cvt_pk_bf16_f32 v93, v93, v109
	v_cvt_pk_bf16_f32 v94, v94, v110
	v_cvt_pk_bf16_f32 v95, v95, v111
	v_cvt_pk_bf16_f32 v96, v96, v112
	v_cvt_pk_bf16_f32 v97, v97, v113
	v_cvt_pk_bf16_f32 v98, v98, v114
	v_cvt_pk_bf16_f32 v99, v99, v115
	s_waitcnt lgkmcnt(0)
	ds_write_b16_d16_hi v56, v92 offset:8704
	ds_write_b16 v56, v92 offset:27136
	ds_write_b16_d16_hi v56, v93 offset:8976
	ds_write_b16 v56, v93 offset:27408
	ds_write_b16_d16_hi v56, v94 offset:9248
	ds_write_b16 v56, v94 offset:27680
	ds_write_b16_d16_hi v56, v95 offset:9520
	ds_write_b16 v56, v95 offset:27952
	ds_write_b16_d16_hi v56, v96 offset:9792
	ds_write_b16 v56, v96 offset:28224
	ds_write_b16_d16_hi v56, v97 offset:10064
	ds_write_b16 v56, v97 offset:28496
	ds_write_b16_d16_hi v56, v98 offset:10336
	ds_write_b16 v56, v98 offset:28768
	ds_write_b16_d16_hi v56, v99 offset:10608
	ds_write_b16 v56, v99 offset:29040
	v_lshlrev_b32_e32 v84, 16, v116
	v_lshlrev_b32_e32 v85, 16, v117
	v_lshlrev_b32_e32 v86, 16, v118
	v_lshlrev_b32_e32 v87, 16, v119
	v_lshlrev_b32_e32 v88, 16, v120
	v_lshlrev_b32_e32 v89, 16, v121
	v_lshlrev_b32_e32 v90, 16, v122
	v_lshlrev_b32_e32 v91, 16, v123
	v_lshlrev_b32_e32 v100, 16, v124
	v_lshlrev_b32_e32 v101, 16, v125
	v_lshlrev_b32_e32 v102, 16, v126
	v_lshlrev_b32_e32 v103, 16, v127
	v_lshlrev_b32_e32 v104, 16, v128
	v_lshlrev_b32_e32 v105, 16, v129
	v_lshlrev_b32_e32 v106, 16, v130
	v_lshlrev_b32_e32 v107, 16, v131
	ds_read_u16 v68, v56 offset:31488
	ds_read_u16 v76, v56 offset:13056
	ds_read_u16 v69, v56 offset:31760
	ds_read_u16 v77, v56 offset:13328
	ds_read_u16 v70, v56 offset:32032
	ds_read_u16 v78, v56 offset:13600
	ds_read_u16 v71, v56 offset:32304
	ds_read_u16 v79, v56 offset:13872
	ds_read_u16 v72, v56 offset:32576
	ds_read_u16 v80, v56 offset:14144
	ds_read_u16 v73, v56 offset:32848
	ds_read_u16 v81, v56 offset:14416
	ds_read_u16 v74, v56 offset:33120
	ds_read_u16 v82, v56 offset:14688
	ds_read_u16 v75, v56 offset:33392
	ds_read_u16 v83, v56 offset:14960
	v_mul_f32_e32 v84, 0xbfb8aa3b, v84
	v_mul_f32_e32 v85, 0xbfb8aa3b, v85
	v_mul_f32_e32 v86, 0xbfb8aa3b, v86
	v_mul_f32_e32 v87, 0xbfb8aa3b, v87
	v_mul_f32_e32 v88, 0xbfb8aa3b, v88
	v_mul_f32_e32 v89, 0xbfb8aa3b, v89
	v_mul_f32_e32 v90, 0xbfb8aa3b, v90
	v_mul_f32_e32 v91, 0xbfb8aa3b, v91
	v_mul_f32_e32 v108, 0xbfb8aa3b, v100
	v_mul_f32_e32 v109, 0xbfb8aa3b, v101
	v_mul_f32_e32 v110, 0xbfb8aa3b, v102
	v_mul_f32_e32 v111, 0xbfb8aa3b, v103
	v_mul_f32_e32 v112, 0xbfb8aa3b, v104
	v_mul_f32_e32 v113, 0xbfb8aa3b, v105
	v_mul_f32_e32 v114, 0xbfb8aa3b, v106
	v_mul_f32_e32 v115, 0xbfb8aa3b, v107
	v_exp_f32_e32 v84, v84
	v_exp_f32_e32 v85, v85
	v_exp_f32_e32 v86, v86
	v_exp_f32_e32 v87, v87
	v_exp_f32_e32 v88, v88
	v_exp_f32_e32 v89, v89
	v_exp_f32_e32 v90, v90
	v_exp_f32_e32 v91, v91
	v_exp_f32_e32 v108, v108
	v_exp_f32_e32 v109, v109
	v_exp_f32_e32 v110, v110
	v_exp_f32_e32 v111, v111
	v_exp_f32_e32 v112, v112
	v_exp_f32_e32 v113, v113
	v_exp_f32_e32 v114, v114
	v_exp_f32_e32 v115, v115
	v_add_f32_e32 v84, 1.0, v84
	v_add_f32_e32 v85, 1.0, v85
	v_add_f32_e32 v86, 1.0, v86
	v_add_f32_e32 v87, 1.0, v87
	v_add_f32_e32 v88, 1.0, v88
	v_add_f32_e32 v89, 1.0, v89
	v_add_f32_e32 v90, 1.0, v90
	v_add_f32_e32 v91, 1.0, v91
	v_add_f32_e32 v108, 1.0, v108
	v_add_f32_e32 v109, 1.0, v109
	v_add_f32_e32 v110, 1.0, v110
	v_add_f32_e32 v111, 1.0, v111
	v_add_f32_e32 v112, 1.0, v112
	v_add_f32_e32 v113, 1.0, v113
	v_add_f32_e32 v114, 1.0, v114
	v_add_f32_e32 v115, 1.0, v115
	v_rcp_f32_e32 v84, v84
	v_rcp_f32_e32 v85, v85
	v_rcp_f32_e32 v86, v86
	v_rcp_f32_e32 v87, v87
	v_rcp_f32_e32 v88, v88
	v_rcp_f32_e32 v89, v89
	v_rcp_f32_e32 v90, v90
	v_rcp_f32_e32 v91, v91
	v_rcp_f32_e32 v108, v108
	v_rcp_f32_e32 v109, v109
	v_rcp_f32_e32 v110, v110
	v_rcp_f32_e32 v111, v111
	v_rcp_f32_e32 v112, v112
	v_rcp_f32_e32 v113, v113
	v_rcp_f32_e32 v114, v114
	v_rcp_f32_e32 v115, v115
	v_sub_f32_e32 v92, 1.0, v84
	v_sub_f32_e32 v93, 1.0, v85
	v_sub_f32_e32 v94, 1.0, v86
	v_sub_f32_e32 v95, 1.0, v87
	v_sub_f32_e32 v96, 1.0, v88
	v_sub_f32_e32 v97, 1.0, v89
	v_sub_f32_e32 v98, 1.0, v90
	v_sub_f32_e32 v99, 1.0, v91
	v_fma_f32 v84, v26, v84, v53
	v_fma_f32 v85, v26, v85, v53
	v_fma_f32 v86, v26, v86, v53
	v_fma_f32 v87, v26, v87, v53
	v_fma_f32 v88, v26, v88, v53
	v_fma_f32 v89, v26, v89, v53
	v_fma_f32 v90, v26, v90, v53
	v_fma_f32 v91, v26, v91, v53
	v_mul_f32_e32 v92, v26, v92
	v_mul_f32_e32 v93, v26, v93
	v_mul_f32_e32 v94, v26, v94
	v_mul_f32_e32 v95, v26, v95
	v_mul_f32_e32 v96, v26, v96
	v_mul_f32_e32 v97, v26, v97
	v_mul_f32_e32 v98, v26, v98
	v_mul_f32_e32 v99, v26, v99
	v_mul_f32_e32 v108, v108, v100
	v_mul_f32_e32 v109, v109, v101
	v_mul_f32_e32 v110, v110, v102
	v_mul_f32_e32 v111, v111, v103
	v_mul_f32_e32 v112, v112, v104
	v_mul_f32_e32 v113, v113, v105
	v_mul_f32_e32 v114, v114, v106
	v_mul_f32_e32 v115, v115, v107
	v_mul_f32_e32 v84, v27, v84
	v_mul_f32_e32 v85, v84, v85
	v_mul_f32_e32 v86, v85, v86
	v_mul_f32_e32 v87, v86, v87
	v_mul_f32_e32 v88, v87, v88
	v_mul_f32_e32 v89, v88, v89
	v_mul_f32_e32 v90, v89, v90
	v_mul_f32_e32 v91, v90, v91
	v_mov_b32_e32 v27, v91
	v_rcp_f32_e32 v100, v84
	v_rcp_f32_e32 v101, v85
	v_rcp_f32_e32 v102, v86
	v_rcp_f32_e32 v103, v87
	v_rcp_f32_e32 v104, v88
	v_rcp_f32_e32 v105, v89
	v_rcp_f32_e32 v106, v90
	v_rcp_f32_e32 v107, v91
	v_mul_f32_e32 v108, v84, v108
	v_mul_f32_e32 v109, v85, v109
	v_mul_f32_e32 v110, v86, v110
	v_mul_f32_e32 v111, v87, v111
	v_mul_f32_e32 v112, v88, v112
	v_mul_f32_e32 v113, v89, v113
	v_mul_f32_e32 v114, v90, v114
	v_mul_f32_e32 v115, v91, v115
	v_mul_f32_e32 v92, v92, v100
	v_mul_f32_e32 v93, v93, v101
	v_mul_f32_e32 v94, v94, v102
	v_mul_f32_e32 v95, v95, v103
	v_mul_f32_e32 v96, v96, v104
	v_mul_f32_e32 v97, v97, v105
	v_mul_f32_e32 v98, v98, v106
	v_mul_f32_e32 v99, v99, v107
	v_cvt_pk_bf16_f32 v92, v92, v108
	v_cvt_pk_bf16_f32 v93, v93, v109
	v_cvt_pk_bf16_f32 v94, v94, v110
	v_cvt_pk_bf16_f32 v95, v95, v111
	v_cvt_pk_bf16_f32 v96, v96, v112
	v_cvt_pk_bf16_f32 v97, v97, v113
	v_cvt_pk_bf16_f32 v98, v98, v114
	v_cvt_pk_bf16_f32 v99, v99, v115
	s_waitcnt lgkmcnt(0)
	ds_write_b16_d16_hi v56, v92 offset:10880
	ds_write_b16 v56, v92 offset:29312
	ds_write_b16_d16_hi v56, v93 offset:11152
	ds_write_b16 v56, v93 offset:29584
	ds_write_b16_d16_hi v56, v94 offset:11424
	ds_write_b16 v56, v94 offset:29856
	ds_write_b16_d16_hi v56, v95 offset:11696
	ds_write_b16 v56, v95 offset:30128
	ds_write_b16_d16_hi v56, v96 offset:11968
	ds_write_b16 v56, v96 offset:30400
	ds_write_b16_d16_hi v56, v97 offset:12240
	ds_write_b16 v56, v97 offset:30672
	ds_write_b16_d16_hi v56, v98 offset:12512
	ds_write_b16 v56, v98 offset:30944
	ds_write_b16_d16_hi v56, v99 offset:12784
	ds_write_b16 v56, v99 offset:31216
	v_lshlrev_b32_e32 v84, 16, v68
	v_lshlrev_b32_e32 v85, 16, v69
	v_lshlrev_b32_e32 v86, 16, v70
	v_lshlrev_b32_e32 v87, 16, v71
	v_lshlrev_b32_e32 v88, 16, v72
	v_lshlrev_b32_e32 v89, 16, v73
	v_lshlrev_b32_e32 v90, 16, v74
	v_lshlrev_b32_e32 v91, 16, v75
	v_lshlrev_b32_e32 v100, 16, v76
	v_lshlrev_b32_e32 v101, 16, v77
	v_lshlrev_b32_e32 v102, 16, v78
	v_lshlrev_b32_e32 v103, 16, v79
	v_lshlrev_b32_e32 v104, 16, v80
	v_lshlrev_b32_e32 v105, 16, v81
	v_lshlrev_b32_e32 v106, 16, v82
	v_lshlrev_b32_e32 v107, 16, v83
	ds_read_u16 v116, v56 offset:33664
	ds_read_u16 v124, v56 offset:15232
	ds_read_u16 v117, v56 offset:33936
	ds_read_u16 v125, v56 offset:15504
	ds_read_u16 v118, v56 offset:34208
	ds_read_u16 v126, v56 offset:15776
	ds_read_u16 v119, v56 offset:34480
	ds_read_u16 v127, v56 offset:16048
	ds_read_u16 v120, v56 offset:34752
	ds_read_u16 v128, v56 offset:16320
	ds_read_u16 v121, v56 offset:35024
	ds_read_u16 v129, v56 offset:16592
	ds_read_u16 v122, v56 offset:35296
	ds_read_u16 v130, v56 offset:16864
	ds_read_u16 v123, v56 offset:35568
	ds_read_u16 v131, v56 offset:17136
	v_mul_f32_e32 v84, 0xbfb8aa3b, v84
	v_mul_f32_e32 v85, 0xbfb8aa3b, v85
	v_mul_f32_e32 v86, 0xbfb8aa3b, v86
	v_mul_f32_e32 v87, 0xbfb8aa3b, v87
	v_mul_f32_e32 v88, 0xbfb8aa3b, v88
	v_mul_f32_e32 v89, 0xbfb8aa3b, v89
	v_mul_f32_e32 v90, 0xbfb8aa3b, v90
	v_mul_f32_e32 v91, 0xbfb8aa3b, v91
	v_mul_f32_e32 v108, 0xbfb8aa3b, v100
	v_mul_f32_e32 v109, 0xbfb8aa3b, v101
	v_mul_f32_e32 v110, 0xbfb8aa3b, v102
	v_mul_f32_e32 v111, 0xbfb8aa3b, v103
	v_mul_f32_e32 v112, 0xbfb8aa3b, v104
	v_mul_f32_e32 v113, 0xbfb8aa3b, v105
	v_mul_f32_e32 v114, 0xbfb8aa3b, v106
	v_mul_f32_e32 v115, 0xbfb8aa3b, v107
	v_exp_f32_e32 v84, v84
	v_exp_f32_e32 v85, v85
	v_exp_f32_e32 v86, v86
	v_exp_f32_e32 v87, v87
	v_exp_f32_e32 v88, v88
	v_exp_f32_e32 v89, v89
	v_exp_f32_e32 v90, v90
	v_exp_f32_e32 v91, v91
	v_exp_f32_e32 v108, v108
	v_exp_f32_e32 v109, v109
	v_exp_f32_e32 v110, v110
	v_exp_f32_e32 v111, v111
	v_exp_f32_e32 v112, v112
	v_exp_f32_e32 v113, v113
	v_exp_f32_e32 v114, v114
	v_exp_f32_e32 v115, v115
	v_add_f32_e32 v84, 1.0, v84
	v_add_f32_e32 v85, 1.0, v85
	v_add_f32_e32 v86, 1.0, v86
	v_add_f32_e32 v87, 1.0, v87
	v_add_f32_e32 v88, 1.0, v88
	v_add_f32_e32 v89, 1.0, v89
	v_add_f32_e32 v90, 1.0, v90
	v_add_f32_e32 v91, 1.0, v91
	v_add_f32_e32 v108, 1.0, v108
	v_add_f32_e32 v109, 1.0, v109
	v_add_f32_e32 v110, 1.0, v110
	v_add_f32_e32 v111, 1.0, v111
	v_add_f32_e32 v112, 1.0, v112
	v_add_f32_e32 v113, 1.0, v113
	v_add_f32_e32 v114, 1.0, v114
	v_add_f32_e32 v115, 1.0, v115
	v_rcp_f32_e32 v84, v84
	v_rcp_f32_e32 v85, v85
	v_rcp_f32_e32 v86, v86
	v_rcp_f32_e32 v87, v87
	v_rcp_f32_e32 v88, v88
	v_rcp_f32_e32 v89, v89
	v_rcp_f32_e32 v90, v90
	v_rcp_f32_e32 v91, v91
	v_rcp_f32_e32 v108, v108
	v_rcp_f32_e32 v109, v109
	v_rcp_f32_e32 v110, v110
	v_rcp_f32_e32 v111, v111
	v_rcp_f32_e32 v112, v112
	v_rcp_f32_e32 v113, v113
	v_rcp_f32_e32 v114, v114
	v_rcp_f32_e32 v115, v115
	v_sub_f32_e32 v92, 1.0, v84
	v_sub_f32_e32 v93, 1.0, v85
	v_sub_f32_e32 v94, 1.0, v86
	v_sub_f32_e32 v95, 1.0, v87
	v_sub_f32_e32 v96, 1.0, v88
	v_sub_f32_e32 v97, 1.0, v89
	v_sub_f32_e32 v98, 1.0, v90
	v_sub_f32_e32 v99, 1.0, v91
	v_fma_f32 v84, v26, v84, v53
	v_fma_f32 v85, v26, v85, v53
	v_fma_f32 v86, v26, v86, v53
	v_fma_f32 v87, v26, v87, v53
	v_fma_f32 v88, v26, v88, v53
	v_fma_f32 v89, v26, v89, v53
	v_fma_f32 v90, v26, v90, v53
	v_fma_f32 v91, v26, v91, v53
	v_mul_f32_e32 v92, v26, v92
	v_mul_f32_e32 v93, v26, v93
	v_mul_f32_e32 v94, v26, v94
	v_mul_f32_e32 v95, v26, v95
	v_mul_f32_e32 v96, v26, v96
	v_mul_f32_e32 v97, v26, v97
	v_mul_f32_e32 v98, v26, v98
	v_mul_f32_e32 v99, v26, v99
	v_mul_f32_e32 v108, v108, v100
	v_mul_f32_e32 v109, v109, v101
	v_mul_f32_e32 v110, v110, v102
	v_mul_f32_e32 v111, v111, v103
	v_mul_f32_e32 v112, v112, v104
	v_mul_f32_e32 v113, v113, v105
	v_mul_f32_e32 v114, v114, v106
	v_mul_f32_e32 v115, v115, v107
	v_mul_f32_e32 v84, v27, v84
	v_mul_f32_e32 v85, v84, v85
	v_mul_f32_e32 v86, v85, v86
	v_mul_f32_e32 v87, v86, v87
	v_mul_f32_e32 v88, v87, v88
	v_mul_f32_e32 v89, v88, v89
	v_mul_f32_e32 v90, v89, v90
	v_mul_f32_e32 v91, v90, v91
	v_mov_b32_e32 v27, v91
	v_rcp_f32_e32 v100, v84
	v_rcp_f32_e32 v101, v85
	v_rcp_f32_e32 v102, v86
	v_rcp_f32_e32 v103, v87
	v_rcp_f32_e32 v104, v88
	v_rcp_f32_e32 v105, v89
	v_rcp_f32_e32 v106, v90
	v_rcp_f32_e32 v107, v91
	v_mul_f32_e32 v108, v84, v108
	v_mul_f32_e32 v109, v85, v109
	v_mul_f32_e32 v110, v86, v110
	v_mul_f32_e32 v111, v87, v111
	v_mul_f32_e32 v112, v88, v112
	v_mul_f32_e32 v113, v89, v113
	v_mul_f32_e32 v114, v90, v114
	v_mul_f32_e32 v115, v91, v115
	v_mul_f32_e32 v92, v92, v100
	v_mul_f32_e32 v93, v93, v101
	v_mul_f32_e32 v94, v94, v102
	v_mul_f32_e32 v95, v95, v103
	v_mul_f32_e32 v96, v96, v104
	v_mul_f32_e32 v97, v97, v105
	v_mul_f32_e32 v98, v98, v106
	v_mul_f32_e32 v99, v99, v107
	v_cvt_pk_bf16_f32 v92, v92, v108
	v_cvt_pk_bf16_f32 v93, v93, v109
	v_cvt_pk_bf16_f32 v94, v94, v110
	v_cvt_pk_bf16_f32 v95, v95, v111
	v_cvt_pk_bf16_f32 v96, v96, v112
	v_cvt_pk_bf16_f32 v97, v97, v113
	v_cvt_pk_bf16_f32 v98, v98, v114
	v_cvt_pk_bf16_f32 v99, v99, v115
	s_waitcnt lgkmcnt(0)
	ds_write_b16_d16_hi v56, v92 offset:13056
	ds_write_b16 v56, v92 offset:31488
	ds_write_b16_d16_hi v56, v93 offset:13328
	ds_write_b16 v56, v93 offset:31760
	ds_write_b16_d16_hi v56, v94 offset:13600
	ds_write_b16 v56, v94 offset:32032
	ds_write_b16_d16_hi v56, v95 offset:13872
	ds_write_b16 v56, v95 offset:32304
	ds_write_b16_d16_hi v56, v96 offset:14144
	ds_write_b16 v56, v96 offset:32576
	ds_write_b16_d16_hi v56, v97 offset:14416
	ds_write_b16 v56, v97 offset:32848
	ds_write_b16_d16_hi v56, v98 offset:14688
	ds_write_b16 v56, v98 offset:33120
	ds_write_b16_d16_hi v56, v99 offset:14960
	ds_write_b16 v56, v99 offset:33392
	v_lshlrev_b32_e32 v84, 16, v116
	v_lshlrev_b32_e32 v85, 16, v117
	v_lshlrev_b32_e32 v86, 16, v118
	v_lshlrev_b32_e32 v87, 16, v119
	v_lshlrev_b32_e32 v88, 16, v120
	v_lshlrev_b32_e32 v89, 16, v121
	v_lshlrev_b32_e32 v90, 16, v122
	v_lshlrev_b32_e32 v91, 16, v123
	v_lshlrev_b32_e32 v100, 16, v124
	v_lshlrev_b32_e32 v101, 16, v125
	v_lshlrev_b32_e32 v102, 16, v126
	v_lshlrev_b32_e32 v103, 16, v127
	v_lshlrev_b32_e32 v104, 16, v128
	v_lshlrev_b32_e32 v105, 16, v129
	v_lshlrev_b32_e32 v106, 16, v130
	v_lshlrev_b32_e32 v107, 16, v131
	v_mul_f32_e32 v84, 0xbfb8aa3b, v84
	v_mul_f32_e32 v85, 0xbfb8aa3b, v85
	v_mul_f32_e32 v86, 0xbfb8aa3b, v86
	v_mul_f32_e32 v87, 0xbfb8aa3b, v87
	v_mul_f32_e32 v88, 0xbfb8aa3b, v88
	v_mul_f32_e32 v89, 0xbfb8aa3b, v89
	v_mul_f32_e32 v90, 0xbfb8aa3b, v90
	v_mul_f32_e32 v91, 0xbfb8aa3b, v91
	v_mul_f32_e32 v108, 0xbfb8aa3b, v100
	v_mul_f32_e32 v109, 0xbfb8aa3b, v101
	v_mul_f32_e32 v110, 0xbfb8aa3b, v102
	v_mul_f32_e32 v111, 0xbfb8aa3b, v103
	v_mul_f32_e32 v112, 0xbfb8aa3b, v104
	v_mul_f32_e32 v113, 0xbfb8aa3b, v105
	v_mul_f32_e32 v114, 0xbfb8aa3b, v106
	v_mul_f32_e32 v115, 0xbfb8aa3b, v107
	v_exp_f32_e32 v84, v84
	v_exp_f32_e32 v85, v85
	v_exp_f32_e32 v86, v86
	v_exp_f32_e32 v87, v87
	v_exp_f32_e32 v88, v88
	v_exp_f32_e32 v89, v89
	v_exp_f32_e32 v90, v90
	v_exp_f32_e32 v91, v91
	v_exp_f32_e32 v108, v108
	v_exp_f32_e32 v109, v109
	v_exp_f32_e32 v110, v110
	v_exp_f32_e32 v111, v111
	v_exp_f32_e32 v112, v112
	v_exp_f32_e32 v113, v113
	v_exp_f32_e32 v114, v114
	v_exp_f32_e32 v115, v115
	v_add_f32_e32 v84, 1.0, v84
	v_add_f32_e32 v85, 1.0, v85
	v_add_f32_e32 v86, 1.0, v86
	v_add_f32_e32 v87, 1.0, v87
	v_add_f32_e32 v88, 1.0, v88
	v_add_f32_e32 v89, 1.0, v89
	v_add_f32_e32 v90, 1.0, v90
	v_add_f32_e32 v91, 1.0, v91
	v_add_f32_e32 v108, 1.0, v108
	v_add_f32_e32 v109, 1.0, v109
	v_add_f32_e32 v110, 1.0, v110
	v_add_f32_e32 v111, 1.0, v111
	v_add_f32_e32 v112, 1.0, v112
	v_add_f32_e32 v113, 1.0, v113
	v_add_f32_e32 v114, 1.0, v114
	v_add_f32_e32 v115, 1.0, v115
	v_rcp_f32_e32 v84, v84
	v_rcp_f32_e32 v85, v85
	v_rcp_f32_e32 v86, v86
	v_rcp_f32_e32 v87, v87
	v_rcp_f32_e32 v88, v88
	v_rcp_f32_e32 v89, v89
	v_rcp_f32_e32 v90, v90
	v_rcp_f32_e32 v91, v91
	v_rcp_f32_e32 v108, v108
	v_rcp_f32_e32 v109, v109
	v_rcp_f32_e32 v110, v110
	v_rcp_f32_e32 v111, v111
	v_rcp_f32_e32 v112, v112
	v_rcp_f32_e32 v113, v113
	v_rcp_f32_e32 v114, v114
	v_rcp_f32_e32 v115, v115
	v_sub_f32_e32 v92, 1.0, v84
	v_sub_f32_e32 v93, 1.0, v85
	v_sub_f32_e32 v94, 1.0, v86
	v_sub_f32_e32 v95, 1.0, v87
	v_sub_f32_e32 v96, 1.0, v88
	v_sub_f32_e32 v97, 1.0, v89
	v_sub_f32_e32 v98, 1.0, v90
	v_sub_f32_e32 v99, 1.0, v91
	v_fma_f32 v84, v26, v84, v53
	v_fma_f32 v85, v26, v85, v53
	v_fma_f32 v86, v26, v86, v53
	v_fma_f32 v87, v26, v87, v53
	v_fma_f32 v88, v26, v88, v53
	v_fma_f32 v89, v26, v89, v53
	v_fma_f32 v90, v26, v90, v53
	v_fma_f32 v91, v26, v91, v53
	v_mul_f32_e32 v92, v26, v92
	v_mul_f32_e32 v93, v26, v93
	v_mul_f32_e32 v94, v26, v94
	v_mul_f32_e32 v95, v26, v95
	v_mul_f32_e32 v96, v26, v96
	v_mul_f32_e32 v97, v26, v97
	v_mul_f32_e32 v98, v26, v98
	v_mul_f32_e32 v99, v26, v99
	v_mul_f32_e32 v108, v108, v100
	v_mul_f32_e32 v109, v109, v101
	v_mul_f32_e32 v110, v110, v102
	v_mul_f32_e32 v111, v111, v103
	v_mul_f32_e32 v112, v112, v104
	v_mul_f32_e32 v113, v113, v105
	v_mul_f32_e32 v114, v114, v106
	v_mul_f32_e32 v115, v115, v107
	v_mul_f32_e32 v84, v27, v84
	v_mul_f32_e32 v85, v84, v85
	v_mul_f32_e32 v86, v85, v86
	v_mul_f32_e32 v87, v86, v87
	v_mul_f32_e32 v88, v87, v88
	v_mul_f32_e32 v89, v88, v89
	v_mul_f32_e32 v90, v89, v90
	v_mul_f32_e32 v91, v90, v91
	v_mov_b32_e32 v27, v91
	v_rcp_f32_e32 v100, v84
	v_rcp_f32_e32 v101, v85
	v_rcp_f32_e32 v102, v86
	v_rcp_f32_e32 v103, v87
	v_rcp_f32_e32 v104, v88
	v_rcp_f32_e32 v105, v89
	v_rcp_f32_e32 v106, v90
	v_rcp_f32_e32 v107, v91
	v_mul_f32_e32 v108, v84, v108
	v_mul_f32_e32 v109, v85, v109
	v_mul_f32_e32 v110, v86, v110
	v_mul_f32_e32 v111, v87, v111
	v_mul_f32_e32 v112, v88, v112
	v_mul_f32_e32 v113, v89, v113
	v_mul_f32_e32 v114, v90, v114
	v_mul_f32_e32 v115, v91, v115
	v_mul_f32_e32 v92, v92, v100
	v_mul_f32_e32 v93, v93, v101
	v_mul_f32_e32 v94, v94, v102
	v_mul_f32_e32 v95, v95, v103
	v_mul_f32_e32 v96, v96, v104
	v_mul_f32_e32 v97, v97, v105
	v_mul_f32_e32 v98, v98, v106
	v_mul_f32_e32 v99, v99, v107
	v_cvt_pk_bf16_f32 v92, v92, v108
	v_cvt_pk_bf16_f32 v93, v93, v109
	v_cvt_pk_bf16_f32 v94, v94, v110
	v_cvt_pk_bf16_f32 v95, v95, v111
	v_cvt_pk_bf16_f32 v96, v96, v112
	v_cvt_pk_bf16_f32 v97, v97, v113
	v_cvt_pk_bf16_f32 v98, v98, v114
	v_cvt_pk_bf16_f32 v99, v99, v115
	s_waitcnt lgkmcnt(0)
	ds_write_b16_d16_hi v56, v92 offset:15232
	ds_write_b16 v56, v92 offset:33664
	ds_write_b16_d16_hi v56, v93 offset:15504
	ds_write_b16 v56, v93 offset:33936
	ds_write_b16_d16_hi v56, v94 offset:15776
	ds_write_b16 v56, v94 offset:34208
	ds_write_b16_d16_hi v56, v95 offset:16048
	ds_write_b16 v56, v95 offset:34480
	ds_write_b16_d16_hi v56, v96 offset:16320
	ds_write_b16 v56, v96 offset:34752
	ds_write_b16_d16_hi v56, v97 offset:16592
	ds_write_b16 v56, v97 offset:35024
	ds_write_b16_d16_hi v56, v98 offset:16864
	ds_write_b16 v56, v98 offset:35296
	ds_write_b16_d16_hi v56, v99 offset:17136
	ds_write_b16 v56, v99 offset:35568
	s_branch .LBB0_900
.Lhp_zero:
	v_mov_b32_e32 v84, 0
	ds_write_b16 v56, v84 offset:4352
	ds_write_b16 v56, v84 offset:22784
	ds_write_b16 v56, v84 offset:4624
	ds_write_b16 v56, v84 offset:23056
	ds_write_b16 v56, v84 offset:4896
	ds_write_b16 v56, v84 offset:23328
	ds_write_b16 v56, v84 offset:5168
	ds_write_b16 v56, v84 offset:23600
	ds_write_b16 v56, v84 offset:5440
	ds_write_b16 v56, v84 offset:23872
	ds_write_b16 v56, v84 offset:5712
	ds_write_b16 v56, v84 offset:24144
	ds_write_b16 v56, v84 offset:5984
	ds_write_b16 v56, v84 offset:24416
	ds_write_b16 v56, v84 offset:6256
	ds_write_b16 v56, v84 offset:24688
	ds_write_b16 v56, v84 offset:6528
	ds_write_b16 v56, v84 offset:24960
	ds_write_b16 v56, v84 offset:6800
	ds_write_b16 v56, v84 offset:25232
	ds_write_b16 v56, v84 offset:7072
	ds_write_b16 v56, v84 offset:25504
	ds_write_b16 v56, v84 offset:7344
	ds_write_b16 v56, v84 offset:25776
	ds_write_b16 v56, v84 offset:7616
	ds_write_b16 v56, v84 offset:26048
	ds_write_b16 v56, v84 offset:7888
	ds_write_b16 v56, v84 offset:26320
	ds_write_b16 v56, v84 offset:8160
	ds_write_b16 v56, v84 offset:26592
	ds_write_b16 v56, v84 offset:8432
	ds_write_b16 v56, v84 offset:26864
	ds_write_b16 v56, v84 offset:8704
	ds_write_b16 v56, v84 offset:27136
	ds_write_b16 v56, v84 offset:8976
	ds_write_b16 v56, v84 offset:27408
	ds_write_b16 v56, v84 offset:9248
	ds_write_b16 v56, v84 offset:27680
	ds_write_b16 v56, v84 offset:9520
	ds_write_b16 v56, v84 offset:27952
	ds_write_b16 v56, v84 offset:9792
	ds_write_b16 v56, v84 offset:28224
	ds_write_b16 v56, v84 offset:10064
	ds_write_b16 v56, v84 offset:28496
	ds_write_b16 v56, v84 offset:10336
	ds_write_b16 v56, v84 offset:28768
	ds_write_b16 v56, v84 offset:10608
	ds_write_b16 v56, v84 offset:29040
	ds_write_b16 v56, v84 offset:10880
	ds_write_b16 v56, v84 offset:29312
	ds_write_b16 v56, v84 offset:11152
	ds_write_b16 v56, v84 offset:29584
	ds_write_b16 v56, v84 offset:11424
	ds_write_b16 v56, v84 offset:29856
	ds_write_b16 v56, v84 offset:11696
	ds_write_b16 v56, v84 offset:30128
	ds_write_b16 v56, v84 offset:11968
	ds_write_b16 v56, v84 offset:30400
	ds_write_b16 v56, v84 offset:12240
	ds_write_b16 v56, v84 offset:30672
	ds_write_b16 v56, v84 offset:12512
	ds_write_b16 v56, v84 offset:30944
	ds_write_b16 v56, v84 offset:12784
	ds_write_b16 v56, v84 offset:31216
	ds_write_b16 v56, v84 offset:13056
	ds_write_b16 v56, v84 offset:31488
	ds_write_b16 v56, v84 offset:13328
	ds_write_b16 v56, v84 offset:31760
	ds_write_b16 v56, v84 offset:13600
	ds_write_b16 v56, v84 offset:32032
	ds_write_b16 v56, v84 offset:13872
	ds_write_b16 v56, v84 offset:32304
	ds_write_b16 v56, v84 offset:14144
	ds_write_b16 v56, v84 offset:32576
	ds_write_b16 v56, v84 offset:14416
	ds_write_b16 v56, v84 offset:32848
	ds_write_b16 v56, v84 offset:14688
	ds_write_b16 v56, v84 offset:33120
	ds_write_b16 v56, v84 offset:14960
	ds_write_b16 v56, v84 offset:33392
	ds_write_b16 v56, v84 offset:15232
	ds_write_b16 v56, v84 offset:33664
	ds_write_b16 v56, v84 offset:15504
	ds_write_b16 v56, v84 offset:33936
	ds_write_b16 v56, v84 offset:15776
	ds_write_b16 v56, v84 offset:34208
	ds_write_b16 v56, v84 offset:16048
	ds_write_b16 v56, v84 offset:34480
	ds_write_b16 v56, v84 offset:16320
	ds_write_b16 v56, v84 offset:34752
	ds_write_b16 v56, v84 offset:16592
	ds_write_b16 v56, v84 offset:35024
	ds_write_b16 v56, v84 offset:16864
	ds_write_b16 v56, v84 offset:35296
	ds_write_b16 v56, v84 offset:17136
	ds_write_b16 v56, v84 offset:35568
